# static s_setprio 1 for waves 0-3 (mirror of the younger-half raise), flips removed
# speedup vs baseline: 1.0028x; 1.0028x over previous
.LBB0_189:
	s_add_u32 s66, s66, 0x100
	s_addc_u32 s67, s67, 0
	s_add_u32 s64, s64, 0x40080
	v_mov_b32_e32 v2, 0
	s_addc_u32 s65, s65, 0
	s_mov_b32 s68, -2
	v_mov_b32_e32 v3, 0
	v_pk_mov_b32 v[4:5], v[2:3], v[2:3]
	v_pk_mov_b32 v[6:7], v[2:3], v[2:3]
	v_pk_mov_b32 v[8:9], v[2:3], v[2:3]
	v_pk_mov_b32 v[10:11], v[2:3], v[2:3]
	v_pk_mov_b32 v[12:13], v[2:3], v[2:3]
	v_pk_mov_b32 v[14:15], v[2:3], v[2:3]
	v_pk_mov_b32 v[16:17], v[2:3], v[2:3]
	v_pk_mov_b32 v[18:19], v[2:3], v[2:3]
	v_pk_mov_b32 v[20:21], v[2:3], v[2:3]
	v_pk_mov_b32 v[22:23], v[2:3], v[2:3]
	v_pk_mov_b32 v[24:25], v[2:3], v[2:3]
	v_pk_mov_b32 v[26:27], v[2:3], v[2:3]
	v_pk_mov_b32 v[28:29], v[2:3], v[2:3]
	v_pk_mov_b32 v[30:31], v[2:3], v[2:3]
	v_pk_mov_b32 v[32:33], v[2:3], v[2:3]
	v_pk_mov_b32 v[34:35], v[2:3], v[2:3]
	v_pk_mov_b32 v[36:37], v[2:3], v[2:3]
	v_pk_mov_b32 v[38:39], v[2:3], v[2:3]
	v_pk_mov_b32 v[40:41], v[2:3], v[2:3]
	v_pk_mov_b32 v[42:43], v[2:3], v[2:3]
	v_pk_mov_b32 v[44:45], v[2:3], v[2:3]
	v_pk_mov_b32 v[46:47], v[2:3], v[2:3]
	v_pk_mov_b32 v[48:49], v[2:3], v[2:3]
	v_pk_mov_b32 v[50:51], v[2:3], v[2:3]
	v_pk_mov_b32 v[52:53], v[2:3], v[2:3]
	v_pk_mov_b32 v[54:55], v[2:3], v[2:3]
	v_pk_mov_b32 v[56:57], v[2:3], v[2:3]
	v_pk_mov_b32 v[58:59], v[2:3], v[2:3]
	v_pk_mov_b32 v[60:61], v[2:3], v[2:3]
	v_pk_mov_b32 v[62:63], v[2:3], v[2:3]
	v_pk_mov_b32 v[64:65], v[2:3], v[2:3]
	v_pk_mov_b32 v[66:67], v[2:3], v[2:3]
	v_pk_mov_b32 v[68:69], v[2:3], v[2:3]
	v_pk_mov_b32 v[70:71], v[2:3], v[2:3]
	v_pk_mov_b32 v[72:73], v[2:3], v[2:3]
	v_pk_mov_b32 v[74:75], v[2:3], v[2:3]
	v_pk_mov_b32 v[76:77], v[2:3], v[2:3]
	v_pk_mov_b32 v[78:79], v[2:3], v[2:3]
	v_pk_mov_b32 v[80:81], v[2:3], v[2:3]
	v_pk_mov_b32 v[82:83], v[2:3], v[2:3]
	v_pk_mov_b32 v[84:85], v[2:3], v[2:3]
	v_pk_mov_b32 v[86:87], v[2:3], v[2:3]
	v_pk_mov_b32 v[88:89], v[2:3], v[2:3]
	v_pk_mov_b32 v[90:91], v[2:3], v[2:3]
	v_pk_mov_b32 v[92:93], v[2:3], v[2:3]
	v_pk_mov_b32 v[94:95], v[2:3], v[2:3]
	v_pk_mov_b32 v[96:97], v[2:3], v[2:3]
	v_pk_mov_b32 v[98:99], v[2:3], v[2:3]
	v_pk_mov_b32 v[100:101], v[2:3], v[2:3]
	v_pk_mov_b32 v[102:103], v[2:3], v[2:3]
	v_pk_mov_b32 v[104:105], v[2:3], v[2:3]
	v_pk_mov_b32 v[106:107], v[2:3], v[2:3]
	v_pk_mov_b32 v[108:109], v[2:3], v[2:3]
	v_pk_mov_b32 v[110:111], v[2:3], v[2:3]
	v_pk_mov_b32 v[112:113], v[2:3], v[2:3]
	v_pk_mov_b32 v[114:115], v[2:3], v[2:3]
	v_pk_mov_b32 v[116:117], v[2:3], v[2:3]
	v_pk_mov_b32 v[118:119], v[2:3], v[2:3]
	v_pk_mov_b32 v[120:121], v[2:3], v[2:3]
	v_pk_mov_b32 v[122:123], v[2:3], v[2:3]
	v_pk_mov_b32 v[124:125], v[2:3], v[2:3]
	v_pk_mov_b32 v[126:127], v[2:3], v[2:3]
	v_pk_mov_b32 v[128:129], v[2:3], v[2:3]
	v_readfirstlane_b32 s100, v0
	s_bitcmp1_b32 s100, 8
	s_cbranch_scc1 .Lsp_p1
	s_setprio 1

.LBB0_1048:
	s_add_u32 s38, s68, 0x100
	s_addc_u32 s68, s69, 0
	s_add_u32 s66, s66, 0x40080
	v_mov_b32_e32 v2, 0
	s_addc_u32 s67, s67, 0
	s_mov_b32 s69, -2
	v_mov_b32_e32 v3, 0
	v_pk_mov_b32 v[4:5], v[2:3], v[2:3]
	v_pk_mov_b32 v[6:7], v[2:3], v[2:3]
	v_pk_mov_b32 v[8:9], v[2:3], v[2:3]
	v_pk_mov_b32 v[10:11], v[2:3], v[2:3]
	v_pk_mov_b32 v[12:13], v[2:3], v[2:3]
	v_pk_mov_b32 v[14:15], v[2:3], v[2:3]
	v_pk_mov_b32 v[16:17], v[2:3], v[2:3]
	v_pk_mov_b32 v[18:19], v[2:3], v[2:3]
	v_pk_mov_b32 v[20:21], v[2:3], v[2:3]
	v_pk_mov_b32 v[22:23], v[2:3], v[2:3]
	v_pk_mov_b32 v[24:25], v[2:3], v[2:3]
	v_pk_mov_b32 v[26:27], v[2:3], v[2:3]
	v_pk_mov_b32 v[28:29], v[2:3], v[2:3]
	v_pk_mov_b32 v[30:31], v[2:3], v[2:3]
	v_pk_mov_b32 v[32:33], v[2:3], v[2:3]
	v_pk_mov_b32 v[34:35], v[2:3], v[2:3]
	v_pk_mov_b32 v[36:37], v[2:3], v[2:3]
	v_pk_mov_b32 v[38:39], v[2:3], v[2:3]
	v_pk_mov_b32 v[40:41], v[2:3], v[2:3]
	v_pk_mov_b32 v[42:43], v[2:3], v[2:3]
	v_pk_mov_b32 v[44:45], v[2:3], v[2:3]
	v_pk_mov_b32 v[46:47], v[2:3], v[2:3]
	v_pk_mov_b32 v[48:49], v[2:3], v[2:3]
	v_pk_mov_b32 v[50:51], v[2:3], v[2:3]
	v_pk_mov_b32 v[52:53], v[2:3], v[2:3]
	v_pk_mov_b32 v[54:55], v[2:3], v[2:3]
	v_pk_mov_b32 v[56:57], v[2:3], v[2:3]
	v_pk_mov_b32 v[58:59], v[2:3], v[2:3]
	v_pk_mov_b32 v[60:61], v[2:3], v[2:3]
	v_pk_mov_b32 v[62:63], v[2:3], v[2:3]
	v_pk_mov_b32 v[64:65], v[2:3], v[2:3]
	v_pk_mov_b32 v[66:67], v[2:3], v[2:3]
	v_pk_mov_b32 v[68:69], v[2:3], v[2:3]
	v_pk_mov_b32 v[70:71], v[2:3], v[2:3]
	v_pk_mov_b32 v[72:73], v[2:3], v[2:3]
	v_pk_mov_b32 v[74:75], v[2:3], v[2:3]
	v_pk_mov_b32 v[76:77], v[2:3], v[2:3]
	v_pk_mov_b32 v[78:79], v[2:3], v[2:3]
	v_pk_mov_b32 v[80:81], v[2:3], v[2:3]
	v_pk_mov_b32 v[82:83], v[2:3], v[2:3]
	v_pk_mov_b32 v[84:85], v[2:3], v[2:3]
	v_pk_mov_b32 v[86:87], v[2:3], v[2:3]
	v_pk_mov_b32 v[88:89], v[2:3], v[2:3]
	v_pk_mov_b32 v[90:91], v[2:3], v[2:3]
	v_pk_mov_b32 v[92:93], v[2:3], v[2:3]
	v_pk_mov_b32 v[94:95], v[2:3], v[2:3]
	v_pk_mov_b32 v[96:97], v[2:3], v[2:3]
	v_pk_mov_b32 v[98:99], v[2:3], v[2:3]
	v_pk_mov_b32 v[100:101], v[2:3], v[2:3]
	v_pk_mov_b32 v[102:103], v[2:3], v[2:3]
	v_pk_mov_b32 v[104:105], v[2:3], v[2:3]
	v_pk_mov_b32 v[106:107], v[2:3], v[2:3]
	v_pk_mov_b32 v[108:109], v[2:3], v[2:3]
	v_pk_mov_b32 v[110:111], v[2:3], v[2:3]
	v_pk_mov_b32 v[112:113], v[2:3], v[2:3]
	v_pk_mov_b32 v[114:115], v[2:3], v[2:3]
	v_pk_mov_b32 v[116:117], v[2:3], v[2:3]
	v_pk_mov_b32 v[118:119], v[2:3], v[2:3]
	v_pk_mov_b32 v[120:121], v[2:3], v[2:3]
	v_pk_mov_b32 v[122:123], v[2:3], v[2:3]
	v_pk_mov_b32 v[124:125], v[2:3], v[2:3]
	v_pk_mov_b32 v[126:127], v[2:3], v[2:3]
	v_pk_mov_b32 v[128:129], v[2:3], v[2:3]
	v_readfirstlane_b32 s100, v0
	s_bitcmp1_b32 s100, 8
	s_cbranch_scc1 .Lsp_p7
	s_setprio 1

.LBB0_1630:
	s_add_u32 s62, s62, 0x100
	s_addc_u32 s63, s63, 0
	s_add_u32 s60, s60, 0x40080
	v_mov_b32_e32 v2, 0
	s_addc_u32 s61, s61, 0
	s_mov_b32 s79, -2
	v_mov_b32_e32 v3, 0
	v_pk_mov_b32 v[4:5], v[2:3], v[2:3]
	v_pk_mov_b32 v[6:7], v[2:3], v[2:3]
	v_pk_mov_b32 v[8:9], v[2:3], v[2:3]
	v_pk_mov_b32 v[10:11], v[2:3], v[2:3]
	v_pk_mov_b32 v[12:13], v[2:3], v[2:3]
	v_pk_mov_b32 v[14:15], v[2:3], v[2:3]
	v_pk_mov_b32 v[16:17], v[2:3], v[2:3]
	v_pk_mov_b32 v[18:19], v[2:3], v[2:3]
	v_pk_mov_b32 v[20:21], v[2:3], v[2:3]
	v_pk_mov_b32 v[22:23], v[2:3], v[2:3]
	v_pk_mov_b32 v[24:25], v[2:3], v[2:3]
	v_pk_mov_b32 v[26:27], v[2:3], v[2:3]
	v_pk_mov_b32 v[28:29], v[2:3], v[2:3]
	v_pk_mov_b32 v[30:31], v[2:3], v[2:3]
	v_pk_mov_b32 v[32:33], v[2:3], v[2:3]
	v_pk_mov_b32 v[34:35], v[2:3], v[2:3]
	v_pk_mov_b32 v[36:37], v[2:3], v[2:3]
	v_pk_mov_b32 v[38:39], v[2:3], v[2:3]
	v_pk_mov_b32 v[40:41], v[2:3], v[2:3]
	v_pk_mov_b32 v[42:43], v[2:3], v[2:3]
	v_pk_mov_b32 v[44:45], v[2:3], v[2:3]
	v_pk_mov_b32 v[46:47], v[2:3], v[2:3]
	v_pk_mov_b32 v[48:49], v[2:3], v[2:3]
	v_pk_mov_b32 v[50:51], v[2:3], v[2:3]
	v_pk_mov_b32 v[52:53], v[2:3], v[2:3]
	v_pk_mov_b32 v[54:55], v[2:3], v[2:3]
	v_pk_mov_b32 v[56:57], v[2:3], v[2:3]
	v_pk_mov_b32 v[58:59], v[2:3], v[2:3]
	v_pk_mov_b32 v[60:61], v[2:3], v[2:3]
	v_pk_mov_b32 v[62:63], v[2:3], v[2:3]
	v_pk_mov_b32 v[64:65], v[2:3], v[2:3]
	v_pk_mov_b32 v[66:67], v[2:3], v[2:3]
	v_pk_mov_b32 v[68:69], v[2:3], v[2:3]
	v_pk_mov_b32 v[70:71], v[2:3], v[2:3]
	v_pk_mov_b32 v[72:73], v[2:3], v[2:3]
	v_pk_mov_b32 v[74:75], v[2:3], v[2:3]
	v_pk_mov_b32 v[76:77], v[2:3], v[2:3]
	v_pk_mov_b32 v[78:79], v[2:3], v[2:3]
	v_pk_mov_b32 v[80:81], v[2:3], v[2:3]
	v_pk_mov_b32 v[82:83], v[2:3], v[2:3]
	v_pk_mov_b32 v[84:85], v[2:3], v[2:3]
	v_pk_mov_b32 v[86:87], v[2:3], v[2:3]
	v_pk_mov_b32 v[88:89], v[2:3], v[2:3]
	v_pk_mov_b32 v[90:91], v[2:3], v[2:3]
	v_pk_mov_b32 v[92:93], v[2:3], v[2:3]
	v_pk_mov_b32 v[94:95], v[2:3], v[2:3]
	v_pk_mov_b32 v[96:97], v[2:3], v[2:3]
	v_pk_mov_b32 v[98:99], v[2:3], v[2:3]
	v_pk_mov_b32 v[100:101], v[2:3], v[2:3]
	v_pk_mov_b32 v[102:103], v[2:3], v[2:3]
	v_pk_mov_b32 v[104:105], v[2:3], v[2:3]
	v_pk_mov_b32 v[106:107], v[2:3], v[2:3]
	v_pk_mov_b32 v[108:109], v[2:3], v[2:3]
	v_pk_mov_b32 v[110:111], v[2:3], v[2:3]
	v_pk_mov_b32 v[112:113], v[2:3], v[2:3]
	v_pk_mov_b32 v[114:115], v[2:3], v[2:3]
	v_pk_mov_b32 v[116:117], v[2:3], v[2:3]
	v_pk_mov_b32 v[118:119], v[2:3], v[2:3]
	v_pk_mov_b32 v[120:121], v[2:3], v[2:3]
	v_pk_mov_b32 v[126:127], v[2:3], v[2:3]
	v_pk_mov_b32 v[128:129], v[2:3], v[2:3]
	v_pk_mov_b32 v[130:131], v[2:3], v[2:3]
	v_pk_mov_b32 v[132:133], v[2:3], v[2:3]
	v_readfirstlane_b32 s100, v0
	s_bitcmp1_b32 s100, 8
	s_cbranch_scc1 .Lsp_p13
	s_setprio 1

.LBB0_1705:
	s_add_u32 s62, s62, 0x100
	s_addc_u32 s63, s63, 0
	s_add_u32 s60, s60, 0x40080
	v_mov_b32_e32 v2, 0
	s_addc_u32 s61, s61, 0
	s_mov_b32 s86, -2
	v_mov_b32_e32 v3, 0
	v_pk_mov_b32 v[4:5], v[2:3], v[2:3]
	v_pk_mov_b32 v[6:7], v[2:3], v[2:3]
	v_pk_mov_b32 v[8:9], v[2:3], v[2:3]
	v_pk_mov_b32 v[10:11], v[2:3], v[2:3]
	v_pk_mov_b32 v[12:13], v[2:3], v[2:3]
	v_pk_mov_b32 v[14:15], v[2:3], v[2:3]
	v_pk_mov_b32 v[16:17], v[2:3], v[2:3]
	v_pk_mov_b32 v[18:19], v[2:3], v[2:3]
	v_pk_mov_b32 v[20:21], v[2:3], v[2:3]
	v_pk_mov_b32 v[22:23], v[2:3], v[2:3]
	v_pk_mov_b32 v[24:25], v[2:3], v[2:3]
	v_pk_mov_b32 v[26:27], v[2:3], v[2:3]
	v_pk_mov_b32 v[28:29], v[2:3], v[2:3]
	v_pk_mov_b32 v[30:31], v[2:3], v[2:3]
	v_pk_mov_b32 v[32:33], v[2:3], v[2:3]
	v_pk_mov_b32 v[34:35], v[2:3], v[2:3]
	v_pk_mov_b32 v[36:37], v[2:3], v[2:3]
	v_pk_mov_b32 v[38:39], v[2:3], v[2:3]
	v_pk_mov_b32 v[40:41], v[2:3], v[2:3]
	v_pk_mov_b32 v[42:43], v[2:3], v[2:3]
	v_pk_mov_b32 v[44:45], v[2:3], v[2:3]
	v_pk_mov_b32 v[46:47], v[2:3], v[2:3]
	v_pk_mov_b32 v[48:49], v[2:3], v[2:3]
	v_pk_mov_b32 v[50:51], v[2:3], v[2:3]
	v_pk_mov_b32 v[52:53], v[2:3], v[2:3]
	v_pk_mov_b32 v[54:55], v[2:3], v[2:3]
	v_pk_mov_b32 v[56:57], v[2:3], v[2:3]
	v_pk_mov_b32 v[58:59], v[2:3], v[2:3]
	v_pk_mov_b32 v[60:61], v[2:3], v[2:3]
	v_pk_mov_b32 v[62:63], v[2:3], v[2:3]
	v_pk_mov_b32 v[64:65], v[2:3], v[2:3]
	v_pk_mov_b32 v[66:67], v[2:3], v[2:3]
	v_pk_mov_b32 v[68:69], v[2:3], v[2:3]
	v_pk_mov_b32 v[70:71], v[2:3], v[2:3]
	v_pk_mov_b32 v[72:73], v[2:3], v[2:3]
	v_pk_mov_b32 v[74:75], v[2:3], v[2:3]
	v_pk_mov_b32 v[76:77], v[2:3], v[2:3]
	v_pk_mov_b32 v[78:79], v[2:3], v[2:3]
	v_pk_mov_b32 v[80:81], v[2:3], v[2:3]
	v_pk_mov_b32 v[82:83], v[2:3], v[2:3]
	v_pk_mov_b32 v[84:85], v[2:3], v[2:3]
	v_pk_mov_b32 v[86:87], v[2:3], v[2:3]
	v_pk_mov_b32 v[88:89], v[2:3], v[2:3]
	v_pk_mov_b32 v[90:91], v[2:3], v[2:3]
	v_pk_mov_b32 v[92:93], v[2:3], v[2:3]
	v_pk_mov_b32 v[94:95], v[2:3], v[2:3]
	v_pk_mov_b32 v[96:97], v[2:3], v[2:3]
	v_pk_mov_b32 v[98:99], v[2:3], v[2:3]
	v_pk_mov_b32 v[100:101], v[2:3], v[2:3]
	v_pk_mov_b32 v[102:103], v[2:3], v[2:3]
	v_pk_mov_b32 v[104:105], v[2:3], v[2:3]
	v_pk_mov_b32 v[106:107], v[2:3], v[2:3]
	v_pk_mov_b32 v[108:109], v[2:3], v[2:3]
	v_pk_mov_b32 v[110:111], v[2:3], v[2:3]
	v_pk_mov_b32 v[112:113], v[2:3], v[2:3]
	v_pk_mov_b32 v[114:115], v[2:3], v[2:3]
	v_pk_mov_b32 v[116:117], v[2:3], v[2:3]
	v_pk_mov_b32 v[118:119], v[2:3], v[2:3]
	v_pk_mov_b32 v[120:121], v[2:3], v[2:3]
	v_pk_mov_b32 v[122:123], v[2:3], v[2:3]
	v_pk_mov_b32 v[124:125], v[2:3], v[2:3]
	v_pk_mov_b32 v[126:127], v[2:3], v[2:3]
	v_pk_mov_b32 v[128:129], v[2:3], v[2:3]
	v_readfirstlane_b32 s100, v0
	s_bitcmp1_b32 s100, 8
	s_cbranch_scc1 .Lsp_p14
	s_setprio 1
